# v049_v043nt
# baseline (speedup 1.0000x reference)
.LBB0_633:
	s_or_b64 exec, exec, s[2:3]
	v_lshl_add_u64 v[30:31], s[48:49], 0, v[18:19]
	v_add_co_u32_e32 v42, vcc, s14, v30
	s_waitcnt vmcnt(0)
	ds_bpermute_b32 v29, v20, v28
	v_addc_co_u32_e32 v43, vcc, 0, v31, vcc
	global_load_dwordx4 v[30:33], v[42:43], off nt
	global_load_dwordx4 v[34:37], v[2:3], off
	global_load_dwordx4 v[38:41], v[2:3], off offset:16
	s_waitcnt lgkmcnt(0)
	v_add_f32_e32 v28, v28, v29
	ds_bpermute_b32 v29, v21, v28
	s_add_i32 s4, s4, s18
	v_lshl_add_u64 v[16:17], v[16:17], 0, s[6:7]
	v_lshl_add_u64 v[18:19], v[18:19], 0, s[8:9]
	s_waitcnt lgkmcnt(0)
	v_add_f32_e32 v28, v28, v29
	ds_bpermute_b32 v29, v22, v28
	s_waitcnt lgkmcnt(0)
	v_add_f32_e32 v28, v28, v29
	ds_bpermute_b32 v29, v23, v28
	s_waitcnt lgkmcnt(0)
	v_add_f32_e32 v28, v28, v29
	ds_bpermute_b32 v29, v24, v28
	s_waitcnt lgkmcnt(0)
	v_add_f32_e32 v28, v28, v29
	ds_bpermute_b32 v29, v25, v28
	s_waitcnt lgkmcnt(0)
	v_add_f32_e32 v28, v28, v29
	v_fmamk_f32 v28, v28, 0x3a000000, v26
	v_mul_f32_e32 v29, 0x4f800000, v28
	v_cmp_gt_f32_e32 vcc, s5, v28
	s_nop 1
	v_cndmask_b32_e32 v28, v28, v29, vcc
	v_sqrt_f32_e32 v29, v28
	s_nop 0
	v_add_u32_e32 v44, -1, v29
	v_add_u32_e32 v45, 1, v29
	v_fma_f32 v46, -v44, v29, v28
	v_fma_f32 v47, -v45, v29, v28
	v_cmp_ge_f32_e64 s[2:3], 0, v46
	s_nop 1
	v_cndmask_b32_e64 v29, v29, v44, s[2:3]
	v_cmp_lt_f32_e64 s[2:3], 0, v47
	s_nop 1
	v_cndmask_b32_e64 v29, v29, v45, s[2:3]
	v_mul_f32_e32 v44, 0x37800000, v29
	v_cndmask_b32_e32 v29, v29, v44, vcc
	v_cmp_class_f32_e32 vcc, v28, v27
	v_lshl_add_u64 v[44:45], s[10:11], 0, v[0:1]
	s_nop 0
	v_cndmask_b32_e32 v28, v29, v28, vcc
	v_div_scale_f32 v29, s[2:3], v28, v28, 1.0
	v_rcp_f32_e32 v46, v29
	v_div_scale_f32 v47, vcc, 1.0, v28, 1.0
	v_fma_f32 v48, -v29, v46, 1.0
	v_fmac_f32_e32 v46, v48, v46
	v_mul_f32_e32 v48, v47, v46
	v_fma_f32 v49, -v29, v48, v47
	v_fmac_f32_e32 v48, v49, v46
	v_fma_f32 v29, -v29, v48, v47
	v_div_fmas_f32 v29, v29, v46, v48
	v_div_fixup_f32 v46, v29, v28, 1.0
	s_waitcnt vmcnt(2)
	v_lshlrev_b32_e32 v28, 16, v30
	v_and_b32_e32 v29, 0xffff0000, v30
	v_lshlrev_b32_e32 v30, 16, v31
	v_and_b32_e32 v31, 0xffff0000, v31
	v_lshlrev_b32_e32 v48, 16, v32
	v_and_b32_e32 v49, 0xffff0000, v32
	v_lshlrev_b32_e32 v32, 16, v33
	v_and_b32_e32 v33, 0xffff0000, v33
	v_pk_mul_f32 v[28:29], v[46:47], v[28:29] op_sel_hi:[0,1]
	v_pk_mul_f32 v[30:31], v[46:47], v[30:31] op_sel_hi:[0,1]
	v_pk_mul_f32 v[48:49], v[46:47], v[48:49] op_sel_hi:[0,1]
	v_pk_mul_f32 v[32:33], v[46:47], v[32:33] op_sel_hi:[0,1]
	s_waitcnt vmcnt(1)
	v_pk_mul_f32 v[30:31], v[36:37], v[30:31]
	v_pk_mul_f32 v[28:29], v[34:35], v[28:29]
	s_waitcnt vmcnt(0)
	v_pk_mul_f32 v[34:35], v[40:41], v[32:33]
	v_pk_mul_f32 v[32:33], v[38:39], v[48:49]
	global_store_dwordx4 v[44:45], v[28:31], off nt
	global_store_dwordx4 v[44:45], v[32:35], off offset:16 nt
	global_load_dwordx4 v[28:31], v[42:43], off offset:1024 nt
	s_nop 0
	global_load_dwordx4 v[32:35], v[6:7], off
	global_load_dwordx4 v[36:39], v[6:7], off offset:16
	v_lshl_add_u64 v[40:41], s[10:11], 0, v[4:5]
	s_waitcnt vmcnt(2)
	v_lshlrev_b32_e32 v44, 16, v28
	v_and_b32_e32 v45, 0xffff0000, v28
	v_lshlrev_b32_e32 v28, 16, v29
	v_and_b32_e32 v29, 0xffff0000, v29
	v_lshlrev_b32_e32 v48, 16, v30
	v_and_b32_e32 v49, 0xffff0000, v30
	v_lshlrev_b32_e32 v30, 16, v31
	v_and_b32_e32 v31, 0xffff0000, v31
	v_pk_mul_f32 v[44:45], v[46:47], v[44:45] op_sel_hi:[0,1]
	v_pk_mul_f32 v[28:29], v[46:47], v[28:29] op_sel_hi:[0,1]
	v_pk_mul_f32 v[48:49], v[46:47], v[48:49] op_sel_hi:[0,1]
	v_pk_mul_f32 v[50:51], v[46:47], v[30:31] op_sel_hi:[0,1]
	s_waitcnt vmcnt(1)
	v_pk_mul_f32 v[30:31], v[34:35], v[28:29]
	v_pk_mul_f32 v[28:29], v[32:33], v[44:45]
	s_waitcnt vmcnt(0)
	v_pk_mul_f32 v[34:35], v[38:39], v[50:51]
	v_pk_mul_f32 v[32:33], v[36:37], v[48:49]
	global_store_dwordx4 v[40:41], v[28:31], off nt
	global_store_dwordx4 v[40:41], v[32:35], off offset:16 nt
	global_load_dwordx4 v[28:31], v[42:43], off offset:2048 nt
	s_nop 0
	global_load_dwordx4 v[32:35], v[10:11], off
	global_load_dwordx4 v[36:39], v[10:11], off offset:16
	v_lshl_add_u64 v[40:41], s[10:11], 0, v[8:9]
	s_waitcnt vmcnt(2)
	v_lshlrev_b32_e32 v44, 16, v28
	v_and_b32_e32 v45, 0xffff0000, v28
	v_lshlrev_b32_e32 v28, 16, v29
	v_and_b32_e32 v29, 0xffff0000, v29
	v_lshlrev_b32_e32 v48, 16, v30
	v_and_b32_e32 v49, 0xffff0000, v30
	v_lshlrev_b32_e32 v30, 16, v31
	v_and_b32_e32 v31, 0xffff0000, v31
	v_pk_mul_f32 v[44:45], v[46:47], v[44:45] op_sel_hi:[0,1]
	v_pk_mul_f32 v[28:29], v[46:47], v[28:29] op_sel_hi:[0,1]
	v_pk_mul_f32 v[48:49], v[46:47], v[48:49] op_sel_hi:[0,1]
	v_pk_mul_f32 v[50:51], v[46:47], v[30:31] op_sel_hi:[0,1]
	s_waitcnt vmcnt(1)
	v_pk_mul_f32 v[30:31], v[34:35], v[28:29]
	v_pk_mul_f32 v[28:29], v[32:33], v[44:45]
	s_waitcnt vmcnt(0)
	v_pk_mul_f32 v[34:35], v[38:39], v[50:51]
	v_pk_mul_f32 v[32:33], v[36:37], v[48:49]
	global_store_dwordx4 v[40:41], v[28:31], off offset:-16 nt
	global_store_dwordx4 v[40:41], v[32:35], off nt
	global_load_dwordx4 v[28:31], v[42:43], off offset:3072 nt
	s_nop 0
	global_load_dwordx4 v[32:35], v[14:15], off
	global_load_dwordx4 v[36:39], v[14:15], off offset:16
	v_lshl_add_u64 v[40:41], s[10:11], 0, v[12:13]
	s_add_u32 s10, s10, s12
	s_addc_u32 s11, s11, s13
	s_cmpk_lt_i32 s4, 0x6000
	s_waitcnt vmcnt(2)
	v_lshlrev_b32_e32 v42, 16, v28
	v_and_b32_e32 v43, 0xffff0000, v28
	v_lshlrev_b32_e32 v28, 16, v29
	v_and_b32_e32 v29, 0xffff0000, v29
	v_lshlrev_b32_e32 v44, 16, v30
	v_and_b32_e32 v45, 0xffff0000, v30
	v_lshlrev_b32_e32 v30, 16, v31
	v_and_b32_e32 v31, 0xffff0000, v31
	v_pk_mul_f32 v[42:43], v[46:47], v[42:43] op_sel_hi:[0,1]
	v_pk_mul_f32 v[28:29], v[46:47], v[28:29] op_sel_hi:[0,1]
	v_pk_mul_f32 v[44:45], v[46:47], v[44:45] op_sel_hi:[0,1]
	v_pk_mul_f32 v[46:47], v[46:47], v[30:31] op_sel_hi:[0,1]
	s_waitcnt vmcnt(1)
	v_pk_mul_f32 v[30:31], v[34:35], v[28:29]
	v_pk_mul_f32 v[28:29], v[32:33], v[42:43]
	s_waitcnt vmcnt(0)
	v_pk_mul_f32 v[34:35], v[38:39], v[46:47]
	v_pk_mul_f32 v[32:33], v[36:37], v[44:45]
	global_store_dwordx4 v[40:41], v[28:31], off offset:-16 nt
	global_store_dwordx4 v[40:41], v[32:35], off nt
	s_cbranch_scc0 .LBB0_636
